# v16 plus cache-warming touch loads for the s5_fused per-item parameters (prefetch; serialized parameter loads then hit L1/L2)
# speedup vs baseline: 1.0098x; 1.0098x over previous
; #define INP(i) ((const float*)(const GASP float*)kargs()[(i)])
; __device__ __forceinline__ void s5_disc(int j, int g, int n, float& ar, float& ai, float& zr, float& zi) {
;     const float step = expf(INP(I_LSTEP)[j * 64 + g]); const int gi = (j * 64 + g) * 64 + n;
;     const float lr = INP(I_LAMRE)[gi], li = INP(I_LAMIM)[gi], mag = expf(lr * step); float sn, cs; sincos_acc(li * step, sn, cs);
;     ar = mag * cs; ai = mag * sn; const float den = lr * lr + li * li, pr = ar - 1.0f, pim = ai; zr = (pr * lr + pim * li) / den; zi = (pim * lr - pr * li) / den;
; __device__ __forceinline__ void s5_fused(const Frame& F, int j) {
;     ...
;     for (int item = F.vcu; item < 256; item += F.G) { const int b = item >> 6, g = item & 63, row0 = b * 2048 + c * 256;
;         u32x2 uf[16];
; #pragma unroll
;         for (int blk = 0; blk < 16; ++blk) uf[blk] = *(const u32x2*)(Z + (size_t)(row0 + blk * 16 + r) * DIN + g * 16 + 4 * kq);
;         float ar, ai, zr0, zi0; s5_disc(j, g, n, ar, ai, zr0, zi0);
.LBB0_1698:
	s_and_b32 s98, s13, 63
	s_or_b32 s98, s98, s30
	v_mbcnt_lo_u32_b32 v250, -1, 0
	v_mbcnt_hi_u32_b32 v250, -1, v250
	v_lshlrev_b32_e32 v250, 6, v250
	s_lshl_b32 s99, s98, 12
	s_load_dwordx2 s[100:101], s[0:1], 0x90
	s_waitcnt lgkmcnt(0)
	s_add_u32 s100, s100, s99
	s_addc_u32 s101, s101, 0
	global_load_dword v251, v250, s[100:101]
	s_load_dwordx2 s[100:101], s[0:1], 0x98
	s_waitcnt lgkmcnt(0)
	s_add_u32 s100, s100, s99
	s_addc_u32 s101, s101, 0
	global_load_dword v251, v250, s[100:101]
	s_load_dwordx2 s[100:101], s[0:1], 0xa0
	s_waitcnt lgkmcnt(0)
	s_add_u32 s100, s100, s99
	s_addc_u32 s101, s101, 0
	global_load_dword v251, v250, s[100:101]
	s_load_dwordx2 s[100:101], s[0:1], 0xa8
	s_waitcnt lgkmcnt(0)
	s_add_u32 s100, s100, s99
	s_addc_u32 s101, s101, 0
	global_load_dword v251, v250, s[100:101]
	v_lshrrev_b32_e32 v250, 4, v250
	s_lshl_b32 s99, s98, 8
	s_load_dwordx2 s[100:101], s[0:1], 0x80
	s_waitcnt lgkmcnt(0)
	s_add_u32 s100, s100, s99
	s_addc_u32 s101, s101, 0
	global_load_dword v251, v250, s[100:101]
	s_load_dwordx2 s[100:101], s[0:1], 0x88
	s_waitcnt lgkmcnt(0)
	s_add_u32 s100, s100, s99
	s_addc_u32 s101, s101, 0
	global_load_dword v251, v250, s[100:101]
	s_lshl_b32 s99, s30, 2
	s_load_dwordx2 s[100:101], s[0:1], 0xb8
	s_waitcnt lgkmcnt(0)
	s_add_u32 s100, s100, s99
	s_addc_u32 s101, s101, 0
	global_load_dword v251, v250, s[100:101]
	s_lshl_b32 s2, s13, 5
	s_and_b32 s28, s13, 63
	s_and_b32 s2, s2, 0xfffff800
	v_add_u32_e32 v130, s2, v145
	s_lshl_b32 s38, s28, 5
	v_lshl_add_u64 v[0:1], v[46:47], 0, s[38:39]
	v_or_b32_e32 v126, 16, v130
	v_or_b32_e32 v122, 32, v130
	v_mad_i64_i32 v[2:3], s[2:3], v130, s87, v[0:1]
	v_mad_i64_i32 v[4:5], s[2:3], v126, s87, v[0:1]
	v_mad_i64_i32 v[6:7], s[2:3], v122, s87, v[0:1]
	v_or_b32_e32 v118, 48, v130
	v_or_b32_e32 v114, 64, v130
	v_or_b32_e32 v110, 0x50, v130
	v_or_b32_e32 v106, 0x60, v130
	v_mad_i64_i32 v[8:9], s[2:3], v118, s87, v[0:1]
	global_load_dwordx2 v[132:133], v[2:3], off
	global_load_dwordx2 v[128:129], v[4:5], off
	global_load_dwordx2 v[124:125], v[6:7], off
	global_load_dwordx2 v[120:121], v[8:9], off
	v_mad_i64_i32 v[2:3], s[2:3], v114, s87, v[0:1]
	v_mad_i64_i32 v[4:5], s[2:3], v110, s87, v[0:1]
	v_mad_i64_i32 v[6:7], s[2:3], v106, s87, v[0:1]
	v_or_b32_e32 v102, 0x70, v130
	v_or_b32_e32 v94, 0x80, v130
	v_or_b32_e32 v90, 0x90, v130
	v_or_b32_e32 v82, 0xa0, v130
	v_mad_i64_i32 v[8:9], s[2:3], v102, s87, v[0:1]
	global_load_dwordx2 v[116:117], v[2:3], off
	global_load_dwordx2 v[112:113], v[4:5], off
	global_load_dwordx2 v[108:109], v[6:7], off
	global_load_dwordx2 v[104:105], v[8:9], off
	v_mad_i64_i32 v[2:3], s[2:3], v94, s87, v[0:1]
	v_mad_i64_i32 v[4:5], s[2:3], v90, s87, v[0:1]
	v_mad_i64_i32 v[6:7], s[2:3], v82, s87, v[0:1]
	v_or_b32_e32 v74, 0xb0, v130
	v_or_b32_e32 v70, 0xc0, v130
	v_or_b32_e32 v62, 0xd0, v130
	v_or_b32_e32 v58, 0xe0, v130
	v_or_b32_e32 v54, 0xf0, v130
	v_mad_i64_i32 v[8:9], s[2:3], v74, s87, v[0:1]
	global_load_dwordx2 v[96:97], v[2:3], off
	global_load_dwordx2 v[92:93], v[4:5], off
	global_load_dwordx2 v[84:85], v[6:7], off
	global_load_dwordx2 v[80:81], v[8:9], off
	v_mad_i64_i32 v[2:3], s[2:3], v70, s87, v[0:1]
	v_mad_i64_i32 v[4:5], s[2:3], v62, s87, v[0:1]
	v_mad_i64_i32 v[6:7], s[2:3], v58, s87, v[0:1]
	v_mad_i64_i32 v[0:1], s[2:3], v54, s87, v[0:1]
	s_mov_b64 s[2:3], s[0:1]
	global_load_dwordx2 v[72:73], v[2:3], off
	global_load_dwordx2 v[64:65], v[4:5], off
	global_load_dwordx2 v[60:61], v[6:7], off
	global_load_dwordx2 v[56:57], v[0:1], off
	s_load_dwordx2 s[16:17], s[2:3], 0xb8
	s_or_b32 s38, s28, s30
	s_lshl_b32 s29, s28, 4
	s_lshl_b64 s[2:3], s[38:39], 2
	s_mov_b64 s[22:23], s[0:1]
	s_waitcnt lgkmcnt(0)
	s_add_u32 s16, s16, s2
	s_addc_u32 s17, s17, s3
	global_load_dword v2, v173, s[16:17]
	s_mov_b64 s[16:17], s[0:1]
	s_load_dwordx2 s[16:17], s[16:17], 0x80
	s_lshl_b32 s11, s38, 6
	v_add_u32_e32 v0, s11, v42
	v_ashrrev_i32_e32 v1, 31, v0
	v_ashrrev_i32_e32 v131, 31, v130
	s_waitcnt lgkmcnt(0)
	v_lshl_add_u64 v[4:5], v[0:1], 2, s[16:17]
	global_load_dword v18, v[4:5], off
	s_load_dwordx2 s[16:17], s[22:23], 0x88
	v_ashrrev_i32_e32 v127, 31, v126
	v_ashrrev_i32_e32 v123, 31, v122
	v_ashrrev_i32_e32 v119, 31, v118
	v_ashrrev_i32_e32 v115, 31, v114
	s_waitcnt lgkmcnt(0)
	v_lshl_add_u64 v[0:1], v[0:1], 2, s[16:17]
	global_load_dword v0, v[0:1], off
	v_ashrrev_i32_e32 v111, 31, v110
	v_ashrrev_i32_e32 v107, 31, v106
	v_ashrrev_i32_e32 v103, 31, v102
	v_ashrrev_i32_e32 v95, 31, v94
	v_ashrrev_i32_e32 v91, 31, v90
	v_ashrrev_i32_e32 v83, 31, v82
	v_ashrrev_i32_e32 v75, 31, v74
	v_ashrrev_i32_e32 v71, 31, v70
	v_ashrrev_i32_e32 v63, 31, v62
	v_ashrrev_i32_e32 v59, 31, v58
	v_ashrrev_i32_e32 v55, 31, v54
	s_waitcnt vmcnt(2)
	v_mul_f32_e32 v1, 0x3fb8aa3b, v2
	v_rndne_f32_e32 v3, v1
	v_fma_f32 v4, v2, s12, -v1
	v_sub_f32_e32 v1, v1, v3
	v_fmac_f32_e32 v4, 0x32a5705f, v2
	v_add_f32_e32 v1, v1, v4
	v_cvt_i32_f32_e32 v3, v3
	v_exp_f32_e32 v1, v1
	v_cmp_ngt_f32_e32 vcc, s14, v2
	v_mov_b32_e32 v4, v175
	v_ldexp_f32 v1, v1, v3
	v_cndmask_b32_e32 v1, 0, v1, vcc
	v_cmp_nlt_f32_e32 vcc, s20, v2
	s_nop 1
	v_cndmask_b32_e32 v19, v221, v1, vcc
	s_waitcnt vmcnt(0)
	v_mul_f32_e32 v3, v19, v0
	v_mul_f32_e32 v0, 0x3f22f983, v3
	v_rndne_f32_e32 v0, v0
	v_fmac_f32_e32 v3, 0xbfc90000, v0
	v_cvt_i32_f32_e32 v1, v0
	v_fmac_f32_e32 v3, 0xb9fda000, v0
	v_fmac_f32_e32 v3, 0xb3a22169, v0
	v_mul_f32_e32 v6, v3, v3
	v_fmamk_f32 v2, v6, 0x3638ef1d, v218
	v_fmamk_f32 v7, v6, 0xb493f27e, v219
	v_and_b32_e32 v0, 3, v1
	v_fmaak_f32 v1, v2, v6, 0x3c088888
	v_fmaak_f32 v2, v7, v6, 0xbab60b61
	v_fmaak_f32 v1, v1, v6, 0xbe2aaaab
	v_fmaak_f32 v2, v2, v6, 0x3d2aaaab
	v_mov_b32_e32 v5, v3
	v_mul_f32_e32 v7, v6, v1
	v_fma_f32 v2, v2, v6, -0.5
	v_pk_fma_f32 v[12:13], v[6:7], v[2:3], v[4:5]
	v_cmp_lt_i32_e32 vcc, 0, v0
	v_mov_b32_e32 v20, v12
	s_and_saveexec_b64 s[22:23], vcc
	s_cbranch_execz .LBB0_1704
	v_cmp_ne_u32_e32 vcc, 1, v0
	v_xor_b32_e32 v20, 0x80000000, v13
	s_and_saveexec_b64 s[16:17], vcc
	s_xor_b64 s[26:27], exec, s[16:17]
	v_cmp_eq_u32_e32 vcc, 2, v0
	s_nop 1
	v_cndmask_b32_e32 v0, v12, v13, vcc
	v_xor_b32_e32 v0, 0x80000000, v0
	v_cndmask_b32_e64 v20, v13, -v12, vcc
	v_mov_b32_e32 v13, v0
	s_andn2_saveexec_b64 s[26:27], s[26:27]
	v_mov_b32_e32 v13, v12
	s_or_b64 exec, exec, s[26:27]

; __global__ void __launch_bounds__(NTHR, 2) fwd_kernel(Args a_unused) {
;     extern __shared__ __attribute__((aligned(16))) unsigned char lds_raw[];
	.amdhsa_kernel _Z10fwd_kernel4Args
		.amdhsa_group_segment_fixed_size 0
		.amdhsa_private_segment_fixed_size 0
		.amdhsa_kernarg_size 584
		.amdhsa_user_sgpr_count 2
		.amdhsa_user_sgpr_dispatch_ptr 0
		.amdhsa_user_sgpr_queue_ptr 0
		.amdhsa_user_sgpr_kernarg_segment_ptr 1
		.amdhsa_user_sgpr_dispatch_id 0
		.amdhsa_user_sgpr_kernarg_preload_length 0
		.amdhsa_user_sgpr_kernarg_preload_offset 0
		.amdhsa_user_sgpr_private_segment_size 0
		.amdhsa_uses_dynamic_stack 0
		.amdhsa_enable_private_segment 0
		.amdhsa_system_sgpr_workgroup_id_x 1
		.amdhsa_system_sgpr_workgroup_id_y 0
		.amdhsa_system_sgpr_workgroup_id_z 0
		.amdhsa_system_sgpr_workgroup_info 0
		.amdhsa_system_vgpr_workitem_id 0
		.amdhsa_next_free_vgpr 252
		.amdhsa_next_free_sgpr 102
		.amdhsa_accum_offset 252
		.amdhsa_reserve_vcc 1
		.amdhsa_float_round_mode_32 0
		.amdhsa_float_round_mode_16_64 0
		.amdhsa_float_denorm_mode_32 3
		.amdhsa_float_denorm_mode_16_64 3
		.amdhsa_dx10_clamp 1
		.amdhsa_ieee_mode 1
		.amdhsa_fp16_overflow 0
		.amdhsa_tg_split 0
		.amdhsa_exception_fp_ieee_invalid_op 0
		.amdhsa_exception_fp_denorm_src 0
		.amdhsa_exception_fp_ieee_div_zero 0
		.amdhsa_exception_fp_ieee_overflow 0
		.amdhsa_exception_fp_ieee_underflow 0
		.amdhsa_exception_fp_ieee_inexact 0
		.amdhsa_exception_int_div_zero 0
	.end_amdhsa_kernel

; __global__ void __launch_bounds__(NTHR, 2) fwd_kernel(Args a_unused) {
;     extern __shared__ __attribute__((aligned(16))) unsigned char lds_raw[];
amdhsa.kernels:
  - .agpr_count:     0
    .args:
      - .offset:         0
        .size:           328
        .value_kind:     by_value
      - .offset:         328
        .size:           4
        .value_kind:     hidden_block_count_x
      - .offset:         332
        .size:           4
        .value_kind:     hidden_block_count_y
      - .offset:         336
        .size:           4
        .value_kind:     hidden_block_count_z
      - .offset:         340
        .size:           2
        .value_kind:     hidden_group_size_x
      - .offset:         342
        .size:           2
        .value_kind:     hidden_group_size_y
      - .offset:         344
        .size:           2
        .value_kind:     hidden_group_size_z
      - .offset:         346
        .size:           2
        .value_kind:     hidden_remainder_x
      - .offset:         348
        .size:           2
        .value_kind:     hidden_remainder_y
      - .offset:         350
        .size:           2
        .value_kind:     hidden_remainder_z
      - .offset:         368
        .size:           8
        .value_kind:     hidden_global_offset_x
      - .offset:         376
        .size:           8
        .value_kind:     hidden_global_offset_y
      - .offset:         384
        .size:           8
        .value_kind:     hidden_global_offset_z
      - .offset:         392
        .size:           2
        .value_kind:     hidden_grid_dims
      - .offset:         448
        .size:           4
        .value_kind:     hidden_dynamic_lds_size
    .group_segment_fixed_size: 0
    .kernarg_segment_align: 8
    .kernarg_segment_size: 584
    .language:       OpenCL C
    .language_version:
      - 2
      - 0
    .max_flat_workgroup_size: 512
    .name:           _Z10fwd_kernel4Args
    .private_segment_fixed_size: 0
    .sgpr_count:     108
    .sgpr_spill_count: 172
    .symbol:         _Z10fwd_kernel4Args.kd
    .uniform_work_group_size: 1
    .uses_dynamic_stack: false
    .vgpr_count:     252
    .vgpr_spill_count: 0
    .wavefront_size: 64
